# w_down EpiRes epilogue: 12-deep pipelined global load/fma/store instead of serialized flat ops
# speedup vs baseline: 1.0069x; 1.0069x over previous
.LBB0_818:
	s_ashr_i32 s26, s57, 31
	s_lshr_b32 s26, s26, 29
	s_add_i32 s26, s57, s26
	s_ashr_i32 s26, s26, 3
	v_lshl_add_u32 v160, s57, 8, v162
	v_lshl_or_b32 v64, s58, 8, v164
	s_mul_hi_i32 s27, s26, 0x6000
	s_mulk_i32 s26, 0x6000
	s_add_u32 s26, s45, s26
	v_ashrrev_i32_e32 v65, 31, v64
	s_addc_u32 s27, s46, s27
	v_lshlrev_b64 v[158:159], 2, v[64:65]
	v_lshlrev_b32_e32 v156, 12, v160
	v_lshl_add_u64 v[64:65], s[26:27], 0, v[158:159]
	v_add_u32_e32 v156, v156, v158
	global_load_dwordx4 v[128:131], v[64:65], off
	global_load_dwordx4 v[116:119], v[64:65], off offset:64
	global_load_dwordx4 v[108:111], v[64:65], off offset:512
	s_nop 0
	global_load_dwordx4 v[64:67], v[64:65], off offset:576
	s_mov_b64 s[26:27], -1
	v_add_u32_e32 v157, 0x10000, v156
	v_add_u32_e32 v158, 0x20000, v156
	v_add_u32_e32 v159, 0x30000, v156
	v_add_u32_e32 v160, 0x80000, v156
	v_add_u32_e32 v161, 0x90000, v156
	v_add_u32_e32 v216, 0xa0000, v156
	v_add_u32_e32 v217, 0xb0000, v156
	global_load_dwordx4 v[168:171], v156, s[2:3]
	global_load_dwordx4 v[172:175], v156, s[2:3] offset:64
	global_load_dwordx4 v[176:179], v156, s[2:3] offset:512
	global_load_dwordx4 v[180:183], v156, s[2:3] offset:576
	global_load_dwordx4 v[184:187], v157, s[2:3]
	global_load_dwordx4 v[188:191], v157, s[2:3] offset:64
	global_load_dwordx4 v[192:195], v157, s[2:3] offset:512
	global_load_dwordx4 v[196:199], v157, s[2:3] offset:576
	global_load_dwordx4 v[200:203], v158, s[2:3]
	global_load_dwordx4 v[204:207], v158, s[2:3] offset:64
	global_load_dwordx4 v[208:211], v158, s[2:3] offset:512
	global_load_dwordx4 v[212:215], v158, s[2:3] offset:576
	s_waitcnt vmcnt(11)
	v_pk_fma_f32 v[140:141], v[140:141], v[128:129], v[168:169]
	v_pk_fma_f32 v[142:143], v[142:143], v[130:131], v[170:171]
	global_store_dwordx4 v156, v[140:143], s[2:3]
	global_load_dwordx4 v[168:171], v159, s[2:3]
	s_waitcnt vmcnt(12)
	v_pk_fma_f32 v[136:137], v[136:137], v[116:117], v[172:173]
	v_pk_fma_f32 v[138:139], v[138:139], v[118:119], v[174:175]
	global_store_dwordx4 v156, v[136:139], s[2:3] offset:64
	global_load_dwordx4 v[172:175], v159, s[2:3] offset:64
	s_waitcnt vmcnt(13)
	v_pk_fma_f32 v[132:133], v[132:133], v[108:109], v[176:177]
	v_pk_fma_f32 v[134:135], v[134:135], v[110:111], v[178:179]
	global_store_dwordx4 v156, v[132:135], s[2:3] offset:512
	global_load_dwordx4 v[176:179], v159, s[2:3] offset:512
	s_waitcnt vmcnt(14)
	v_pk_fma_f32 v[124:125], v[124:125], v[64:65], v[180:181]
	v_pk_fma_f32 v[126:127], v[126:127], v[66:67], v[182:183]
	global_store_dwordx4 v156, v[124:127], s[2:3] offset:576
	global_load_dwordx4 v[180:183], v159, s[2:3] offset:576
	s_waitcnt vmcnt(15)
	v_pk_fma_f32 v[120:121], v[120:121], v[128:129], v[184:185]
	v_pk_fma_f32 v[122:123], v[122:123], v[130:131], v[186:187]
	global_store_dwordx4 v157, v[120:123], s[2:3]
	global_load_dwordx4 v[184:187], v160, s[2:3]
	s_waitcnt vmcnt(16)
	v_pk_fma_f32 v[112:113], v[112:113], v[116:117], v[188:189]
	v_pk_fma_f32 v[114:115], v[114:115], v[118:119], v[190:191]
	global_store_dwordx4 v157, v[112:115], s[2:3] offset:64
	global_load_dwordx4 v[188:191], v160, s[2:3] offset:64
	s_waitcnt vmcnt(17)
	v_pk_fma_f32 v[104:105], v[104:105], v[108:109], v[192:193]
	v_pk_fma_f32 v[106:107], v[106:107], v[110:111], v[194:195]
	global_store_dwordx4 v157, v[104:107], s[2:3] offset:512
	global_load_dwordx4 v[192:195], v160, s[2:3] offset:512
	s_waitcnt vmcnt(18)
	v_pk_fma_f32 v[100:101], v[100:101], v[64:65], v[196:197]
	v_pk_fma_f32 v[102:103], v[102:103], v[66:67], v[198:199]
	global_store_dwordx4 v157, v[100:103], s[2:3] offset:576
	global_load_dwordx4 v[196:199], v160, s[2:3] offset:576
	s_waitcnt vmcnt(19)
	v_pk_fma_f32 v[96:97], v[96:97], v[128:129], v[200:201]
	v_pk_fma_f32 v[98:99], v[98:99], v[130:131], v[202:203]
	global_store_dwordx4 v158, v[96:99], s[2:3]
	global_load_dwordx4 v[200:203], v161, s[2:3]
	s_waitcnt vmcnt(20)
	v_pk_fma_f32 v[92:93], v[92:93], v[116:117], v[204:205]
	v_pk_fma_f32 v[94:95], v[94:95], v[118:119], v[206:207]
	global_store_dwordx4 v158, v[92:95], s[2:3] offset:64
	global_load_dwordx4 v[204:207], v161, s[2:3] offset:64
	s_waitcnt vmcnt(21)
	v_pk_fma_f32 v[88:89], v[88:89], v[108:109], v[208:209]
	v_pk_fma_f32 v[90:91], v[90:91], v[110:111], v[210:211]
	global_store_dwordx4 v158, v[88:91], s[2:3] offset:512
	global_load_dwordx4 v[208:211], v161, s[2:3] offset:512
	s_waitcnt vmcnt(22)
	v_pk_fma_f32 v[84:85], v[84:85], v[64:65], v[212:213]
	v_pk_fma_f32 v[86:87], v[86:87], v[66:67], v[214:215]
	global_store_dwordx4 v158, v[84:87], s[2:3] offset:576
	global_load_dwordx4 v[212:215], v161, s[2:3] offset:576
	s_waitcnt vmcnt(22)
	v_pk_fma_f32 v[80:81], v[80:81], v[128:129], v[168:169]
	v_pk_fma_f32 v[82:83], v[82:83], v[130:131], v[170:171]
	global_store_dwordx4 v159, v[80:83], s[2:3]
	global_load_dwordx4 v[168:171], v216, s[2:3]
	s_waitcnt vmcnt(22)
	v_pk_fma_f32 v[76:77], v[76:77], v[116:117], v[172:173]
	v_pk_fma_f32 v[78:79], v[78:79], v[118:119], v[174:175]
	global_store_dwordx4 v159, v[76:79], s[2:3] offset:64
	global_load_dwordx4 v[172:175], v216, s[2:3] offset:64
	s_waitcnt vmcnt(22)
	v_pk_fma_f32 v[72:73], v[72:73], v[108:109], v[176:177]
	v_pk_fma_f32 v[74:75], v[74:75], v[110:111], v[178:179]
	global_store_dwordx4 v159, v[72:75], s[2:3] offset:512
	global_load_dwordx4 v[176:179], v216, s[2:3] offset:512
	s_waitcnt vmcnt(22)
	v_pk_fma_f32 v[68:69], v[68:69], v[64:65], v[180:181]
	v_pk_fma_f32 v[70:71], v[70:71], v[66:67], v[182:183]
	global_store_dwordx4 v159, v[68:71], s[2:3] offset:576
	global_load_dwordx4 v[180:183], v216, s[2:3] offset:576
	s_waitcnt vmcnt(22)
	v_pk_fma_f32 v[60:61], v[60:61], v[128:129], v[184:185]
	v_pk_fma_f32 v[62:63], v[62:63], v[130:131], v[186:187]
	global_store_dwordx4 v160, v[60:63], s[2:3]
	global_load_dwordx4 v[184:187], v217, s[2:3]
	s_waitcnt vmcnt(22)
	v_pk_fma_f32 v[56:57], v[56:57], v[116:117], v[188:189]
	v_pk_fma_f32 v[58:59], v[58:59], v[118:119], v[190:191]
	global_store_dwordx4 v160, v[56:59], s[2:3] offset:64
	global_load_dwordx4 v[188:191], v217, s[2:3] offset:64
	s_waitcnt vmcnt(22)
	v_pk_fma_f32 v[52:53], v[52:53], v[108:109], v[192:193]
	v_pk_fma_f32 v[54:55], v[54:55], v[110:111], v[194:195]
	global_store_dwordx4 v160, v[52:55], s[2:3] offset:512
	global_load_dwordx4 v[192:195], v217, s[2:3] offset:512
	s_waitcnt vmcnt(22)
	v_pk_fma_f32 v[48:49], v[48:49], v[64:65], v[196:197]
	v_pk_fma_f32 v[50:51], v[50:51], v[66:67], v[198:199]
	global_store_dwordx4 v160, v[48:51], s[2:3] offset:576
	global_load_dwordx4 v[196:199], v217, s[2:3] offset:576
	s_waitcnt vmcnt(22)
	v_pk_fma_f32 v[44:45], v[44:45], v[128:129], v[200:201]
	v_pk_fma_f32 v[46:47], v[46:47], v[130:131], v[202:203]
	global_store_dwordx4 v161, v[44:47], s[2:3]
	s_waitcnt vmcnt(21)
	v_pk_fma_f32 v[40:41], v[40:41], v[116:117], v[204:205]
	v_pk_fma_f32 v[42:43], v[42:43], v[118:119], v[206:207]
	global_store_dwordx4 v161, v[40:43], s[2:3] offset:64
	s_waitcnt vmcnt(20)
	v_pk_fma_f32 v[36:37], v[36:37], v[108:109], v[208:209]
	v_pk_fma_f32 v[38:39], v[38:39], v[110:111], v[210:211]
	global_store_dwordx4 v161, v[36:39], s[2:3] offset:512
	s_waitcnt vmcnt(19)
	v_pk_fma_f32 v[32:33], v[32:33], v[64:65], v[212:213]
	v_pk_fma_f32 v[34:35], v[34:35], v[66:67], v[214:215]
	global_store_dwordx4 v161, v[32:35], s[2:3] offset:576
	s_waitcnt vmcnt(18)
	v_pk_fma_f32 v[28:29], v[28:29], v[128:129], v[168:169]
	v_pk_fma_f32 v[30:31], v[30:31], v[130:131], v[170:171]
	global_store_dwordx4 v216, v[28:31], s[2:3]
	s_waitcnt vmcnt(17)
	v_pk_fma_f32 v[24:25], v[24:25], v[116:117], v[172:173]
	v_pk_fma_f32 v[26:27], v[26:27], v[118:119], v[174:175]
	global_store_dwordx4 v216, v[24:27], s[2:3] offset:64
	s_waitcnt vmcnt(16)
	v_pk_fma_f32 v[20:21], v[20:21], v[108:109], v[176:177]
	v_pk_fma_f32 v[22:23], v[22:23], v[110:111], v[178:179]
	global_store_dwordx4 v216, v[20:23], s[2:3] offset:512
	s_waitcnt vmcnt(15)
	v_pk_fma_f32 v[16:17], v[16:17], v[64:65], v[180:181]
	v_pk_fma_f32 v[18:19], v[18:19], v[66:67], v[182:183]
	global_store_dwordx4 v216, v[16:19], s[2:3] offset:576
	s_waitcnt vmcnt(14)
	v_pk_fma_f32 v[12:13], v[12:13], v[128:129], v[184:185]
	v_pk_fma_f32 v[14:15], v[14:15], v[130:131], v[186:187]
	global_store_dwordx4 v217, v[12:15], s[2:3]
	s_waitcnt vmcnt(13)
	v_pk_fma_f32 v[8:9], v[8:9], v[116:117], v[188:189]
	v_pk_fma_f32 v[10:11], v[10:11], v[118:119], v[190:191]
	global_store_dwordx4 v217, v[8:11], s[2:3] offset:64
	s_waitcnt vmcnt(12)
	v_pk_fma_f32 v[4:5], v[4:5], v[108:109], v[192:193]
	v_pk_fma_f32 v[6:7], v[6:7], v[110:111], v[194:195]
	global_store_dwordx4 v217, v[4:7], s[2:3] offset:512
	s_waitcnt vmcnt(11)
	v_pk_fma_f32 v[0:1], v[0:1], v[64:65], v[196:197]
	v_pk_fma_f32 v[2:3], v[2:3], v[66:67], v[198:199]
	global_store_dwordx4 v217, v[0:3], s[2:3] offset:576
	s_andn2_b64 vcc, exec, s[0:1]
	s_cbranch_vccnz .LBB0_807
	s_andn2_b64 vcc, exec, s[6:7]
	s_cbranch_vccnz .LBB0_806
	s_barrier
	s_branch .LBB0_806
